# SSM pass 1 stages only the 32 W8 fragments it uses (32 KiB) instead of all 96
# speedup vs baseline: 1.0156x; 1.0004x over previous
; #define LAS __attribute__((address_space(3)))
; template <bool PASS2>
; __device__ __forceinline__ void ssm_phase(const Params& p, const Frame& F0) {
;     ...
;         { const u32x4* src = (const u32x4*)((const bf16_t*)(p.ws + WS_SSMW) + (size_t)g * SSM_FRAG_ELEMS);
;           for (int e = F.tid; e < SSM_FRAG_ELEMS / 8; e += 512) ((LAS u32x4*)F.lds)[e] = src[e];
;           if (F.tid < 64) ((LAS f32x2*)(F.lds + SSM_M1_OFF))[F.tid] = ((const f32x2*)(p.ws + WS_M1))[g * 64 + F.tid]; }
.LBB0_523:
	global_load_dwordx4 v[4:7], v[0:1], off
	v_lshl_add_u64 v[0:1], v[0:1], 0, s[14:15]
	global_load_dwordx4 v[8:11], v[0:1], off
	v_lshl_add_u64 v[0:1], v[0:1], 0, s[14:15]
	global_load_dwordx4 v[12:15], v[0:1], off
	v_lshl_add_u64 v[0:1], v[0:1], 0, s[14:15]
	global_load_dwordx4 v[16:19], v[0:1], off
	s_waitcnt vmcnt(3)
	ds_write_b128 v2, v[4:7]
	s_waitcnt vmcnt(2)
	ds_write_b128 v2, v[8:11] offset:8192
	s_waitcnt vmcnt(1)
	ds_write_b128 v2, v[12:15] offset:16384
	s_waitcnt vmcnt(0)
	ds_write_b128 v2, v[16:19] offset:24576
